# non-leader workgroups poll the cross-XCD release generation directly instead of the per-XCD relay word (one fewer hop per grid barrier)
# speedup vs baseline: 1.0044x; 1.0044x over previous
; __device__ __forceinline__ unsigned xb_ld(unsigned* p)              { return __hip_atomic_load(p, __ATOMIC_RELAXED, __HIP_MEMORY_SCOPE_AGENT); }
; __device__ __forceinline__ unsigned xb_add(unsigned* p, unsigned v) { return __hip_atomic_fetch_add(p, v, __ATOMIC_RELAXED, __HIP_MEMORY_SCOPE_AGENT); }
; #define XB_SPIN(cond, bar) do { unsigned _sp = 0; while (cond) { __builtin_amdgcn_s_sleep(1); \
;     if ((++_sp & 255u) == 0u) { if (xb_ld(&(bar)[XB_TMO])) break; if (_sp > XB_SPIN_CAP) { atomicAdd(&(bar)[XB_TMO], 1u); break; } } } } while (0)
; __device__ __forceinline__ void xcd_barrier(const XcdBarrier& b) {
;     ...
;         const unsigned old = xb_add(&bar[XB_XSUB(b.x)], 1u);
;         const unsigned gen = old / nloc;
;         if (old + 1u == (gen + 1u) * nloc) {
;             __builtin_amdgcn_fence(__ATOMIC_RELEASE, "agent");
;             asm volatile("s_waitcnt vmcnt(0)" ::: "memory");
;             const unsigned og = xb_add(&bar[XB_TOP], 1u);
;             const unsigned tg = og / nx;
;             if (og + 1u == (tg + 1u) * nx) xb_add(&bar[XB_TOPGEN], 1u);
;             else XB_SPIN(xb_ld(&bar[XB_TOPGEN]) == tg, bar);
;             __builtin_amdgcn_fence(__ATOMIC_ACQUIRE, "agent");
;             xb_add(&bar[XB_XGEN(b.x)], 1u);
;             asm volatile("s_waitcnt vmcnt(0)" ::: "memory");
;         } else {
;             XB_SPIN(xb_ld(&bar[XB_XGEN(b.x)]) == gen, bar);
.LBB0_433:
	s_or_b64 exec, exec, s[8:9]
	v_cvt_f32_u32_e32 v4, v2
	s_waitcnt vmcnt(0)
	v_readfirstlane_b32 s6, v3
	v_sub_u32_e32 v3, 0, v2
	v_rcp_iflag_f32_e32 v4, v4
	v_add_u32_e32 v5, s6, v1
	v_mul_f32_e32 v4, 0x4f7ffffe, v4
	v_cvt_u32_f32_e32 v4, v4
	v_mul_lo_u32 v1, v3, v4
	v_mul_hi_u32 v1, v4, v1
	v_add_u32_e32 v1, v4, v1
	v_mul_hi_u32 v1, v5, v1
	v_mul_lo_u32 v3, v1, v2
	v_sub_u32_e32 v3, v5, v3
	v_add_u32_e32 v4, 1, v1
	v_cmp_ge_u32_e32 vcc, v3, v2
	s_nop 1
	v_cndmask_b32_e32 v1, v1, v4, vcc
	v_sub_u32_e32 v4, v3, v2
	v_cndmask_b32_e32 v3, v3, v4, vcc
	v_add_u32_e32 v4, 1, v1
	v_cmp_ge_u32_e32 vcc, v3, v2
	v_add_u32_e32 v3, 1, v5
	s_nop 0
	v_cndmask_b32_e32 v1, v1, v4, vcc
	v_mul_lo_u32 v4, v2, v1
	v_add_u32_e32 v2, v4, v2
	v_cmp_ne_u32_e32 vcc, v3, v2
	s_and_saveexec_b64 s[6:7], vcc
	s_xor_b64 s[6:7], exec, s[6:7]
	s_cbranch_execz .LBB0_447
	s_waitcnt lgkmcnt(0)
	v_mov_b32_e32 v0, 0x3000
	global_load_dword v0, v0, s[28:29] offset:1280 sc1
	s_add_u32 s10, s28, 0x3500
	s_addc_u32 s11, s29, 0
	s_waitcnt vmcnt(0)
	v_cmp_eq_u32_e32 vcc, v0, v1
	s_and_saveexec_b64 s[8:9], vcc
	s_cbranch_execz .LBB0_446
	s_mov_b32 s18, 1
	s_mov_b64 s[12:13], 0
	v_mov_b32_e32 v0, 0
	s_branch .LBB0_437

; __device__ __forceinline__ unsigned xb_ld(unsigned* p)              { return __hip_atomic_load(p, __ATOMIC_RELAXED, __HIP_MEMORY_SCOPE_AGENT); }
; __device__ __forceinline__ unsigned xb_add(unsigned* p, unsigned v) { return __hip_atomic_fetch_add(p, v, __ATOMIC_RELAXED, __HIP_MEMORY_SCOPE_AGENT); }
; #define XB_SPIN(cond, bar) do { unsigned _sp = 0; while (cond) { __builtin_amdgcn_s_sleep(1); \
;     if ((++_sp & 255u) == 0u) { if (xb_ld(&(bar)[XB_TMO])) break; if (_sp > XB_SPIN_CAP) { atomicAdd(&(bar)[XB_TMO], 1u); break; } } } } while (0)
; __device__ __forceinline__ void xcd_barrier(const XcdBarrier& b) {
;     ...
;         const unsigned old = xb_add(&bar[XB_XSUB(b.x)], 1u);
;         const unsigned gen = old / nloc;
;         if (old + 1u == (gen + 1u) * nloc) {
;             __builtin_amdgcn_fence(__ATOMIC_RELEASE, "agent");
;             asm volatile("s_waitcnt vmcnt(0)" ::: "memory");
;             const unsigned og = xb_add(&bar[XB_TOP], 1u);
;             const unsigned tg = og / nx;
;             if (og + 1u == (tg + 1u) * nx) xb_add(&bar[XB_TOPGEN], 1u);
;             else XB_SPIN(xb_ld(&bar[XB_TOPGEN]) == tg, bar);
;             __builtin_amdgcn_fence(__ATOMIC_ACQUIRE, "agent");
;             xb_add(&bar[XB_XGEN(b.x)], 1u);
;             asm volatile("s_waitcnt vmcnt(0)" ::: "memory");
;         } else {
;             XB_SPIN(xb_ld(&bar[XB_XGEN(b.x)]) == gen, bar);
.LBB0_1044:
	s_or_b64 exec, exec, s[12:13]
	v_cvt_f32_u32_e32 v4, v2
	s_waitcnt vmcnt(0)
	v_readfirstlane_b32 s6, v3
	v_sub_u32_e32 v3, 0, v2
	v_rcp_iflag_f32_e32 v4, v4
	v_add_u32_e32 v5, s6, v1
	v_mul_f32_e32 v4, 0x4f7ffffe, v4
	v_cvt_u32_f32_e32 v4, v4
	v_mul_lo_u32 v1, v3, v4
	v_mul_hi_u32 v1, v4, v1
	v_add_u32_e32 v1, v4, v1
	v_mul_hi_u32 v1, v5, v1
	v_mul_lo_u32 v3, v1, v2
	v_sub_u32_e32 v3, v5, v3
	v_add_u32_e32 v4, 1, v1
	v_cmp_ge_u32_e32 vcc, v3, v2
	s_nop 1
	v_cndmask_b32_e32 v1, v1, v4, vcc
	v_sub_u32_e32 v4, v3, v2
	v_cndmask_b32_e32 v3, v3, v4, vcc
	v_add_u32_e32 v4, 1, v1
	v_cmp_ge_u32_e32 vcc, v3, v2
	v_add_u32_e32 v3, 1, v5
	s_nop 0
	v_cndmask_b32_e32 v1, v1, v4, vcc
	v_mul_lo_u32 v4, v2, v1
	v_add_u32_e32 v2, v4, v2
	v_cmp_ne_u32_e32 vcc, v3, v2
	s_and_saveexec_b64 s[6:7], vcc
	s_xor_b64 s[6:7], exec, s[6:7]
	s_cbranch_execz .LBB0_1058
	s_waitcnt lgkmcnt(0)
	v_mov_b32_e32 v0, 0x3000
	global_load_dword v0, v0, s[28:29] offset:1280 sc1
	s_add_u32 s14, s28, 0x3500
	s_addc_u32 s15, s29, 0
	s_waitcnt vmcnt(0)
	v_cmp_eq_u32_e32 vcc, v0, v1
	s_and_saveexec_b64 s[12:13], vcc
	s_cbranch_execz .LBB0_1057
	s_mov_b32 s18, 1
	s_mov_b64 s[16:17], 0
	v_mov_b32_e32 v0, 0
	s_branch .LBB0_1048

; __device__ __forceinline__ unsigned xb_ld(unsigned* p)              { return __hip_atomic_load(p, __ATOMIC_RELAXED, __HIP_MEMORY_SCOPE_AGENT); }
; __device__ __forceinline__ unsigned xb_add(unsigned* p, unsigned v) { return __hip_atomic_fetch_add(p, v, __ATOMIC_RELAXED, __HIP_MEMORY_SCOPE_AGENT); }
; #define XB_SPIN(cond, bar) do { unsigned _sp = 0; while (cond) { __builtin_amdgcn_s_sleep(1); \
;     if ((++_sp & 255u) == 0u) { if (xb_ld(&(bar)[XB_TMO])) break; if (_sp > XB_SPIN_CAP) { atomicAdd(&(bar)[XB_TMO], 1u); break; } } } } while (0)
; __device__ __forceinline__ void xcd_barrier(const XcdBarrier& b) {
;     ...
;         const unsigned old = xb_add(&bar[XB_XSUB(b.x)], 1u);
;         const unsigned gen = old / nloc;
;         if (old + 1u == (gen + 1u) * nloc) {
;             __builtin_amdgcn_fence(__ATOMIC_RELEASE, "agent");
;             asm volatile("s_waitcnt vmcnt(0)" ::: "memory");
;             const unsigned og = xb_add(&bar[XB_TOP], 1u);
;             const unsigned tg = og / nx;
;             if (og + 1u == (tg + 1u) * nx) xb_add(&bar[XB_TOPGEN], 1u);
;             else XB_SPIN(xb_ld(&bar[XB_TOPGEN]) == tg, bar);
;             __builtin_amdgcn_fence(__ATOMIC_ACQUIRE, "agent");
;             xb_add(&bar[XB_XGEN(b.x)], 1u);
;             asm volatile("s_waitcnt vmcnt(0)" ::: "memory");
;         } else {
;             XB_SPIN(xb_ld(&bar[XB_XGEN(b.x)]) == gen, bar);
.LBB0_1481:
	s_or_b64 exec, exec, s[6:7]
	v_cvt_f32_u32_e32 v4, v2
	s_waitcnt vmcnt(0)
	v_readfirstlane_b32 s4, v3
	v_sub_u32_e32 v3, 0, v2
	v_rcp_iflag_f32_e32 v4, v4
	v_add_u32_e32 v5, s4, v1
	v_mul_f32_e32 v4, 0x4f7ffffe, v4
	v_cvt_u32_f32_e32 v4, v4
	v_mul_lo_u32 v1, v3, v4
	v_mul_hi_u32 v1, v4, v1
	v_add_u32_e32 v1, v4, v1
	v_mul_hi_u32 v1, v5, v1
	v_mul_lo_u32 v3, v1, v2
	v_sub_u32_e32 v3, v5, v3
	v_add_u32_e32 v4, 1, v1
	v_cmp_ge_u32_e32 vcc, v3, v2
	s_nop 1
	v_cndmask_b32_e32 v1, v1, v4, vcc
	v_sub_u32_e32 v4, v3, v2
	v_cndmask_b32_e32 v3, v3, v4, vcc
	v_add_u32_e32 v4, 1, v1
	v_cmp_ge_u32_e32 vcc, v3, v2
	v_add_u32_e32 v3, 1, v5
	s_nop 0
	v_cndmask_b32_e32 v1, v1, v4, vcc
	v_mul_lo_u32 v4, v2, v1
	v_add_u32_e32 v2, v4, v2
	v_cmp_ne_u32_e32 vcc, v3, v2
	s_and_saveexec_b64 s[4:5], vcc
	s_xor_b64 s[4:5], exec, s[4:5]
	s_cbranch_execz .LBB0_1495
	s_waitcnt lgkmcnt(0)
	v_mov_b32_e32 v0, 0x3000
	global_load_dword v0, v0, s[28:29] offset:1280 sc1
	s_add_u32 s12, s28, 0x3500
	s_addc_u32 s13, s29, 0
	s_waitcnt vmcnt(0)
	v_cmp_eq_u32_e32 vcc, v0, v1
	s_and_saveexec_b64 s[6:7], vcc
	s_cbranch_execz .LBB0_1494
	s_mov_b32 s18, 1
	s_mov_b64 s[14:15], 0
	v_mov_b32_e32 v0, 0
	s_branch .LBB0_1485

; __device__ __forceinline__ unsigned xb_ld(unsigned* p)              { return __hip_atomic_load(p, __ATOMIC_RELAXED, __HIP_MEMORY_SCOPE_AGENT); }
; __device__ __forceinline__ unsigned xb_add(unsigned* p, unsigned v) { return __hip_atomic_fetch_add(p, v, __ATOMIC_RELAXED, __HIP_MEMORY_SCOPE_AGENT); }
; #define XB_SPIN(cond, bar) do { unsigned _sp = 0; while (cond) { __builtin_amdgcn_s_sleep(1); \
;     if ((++_sp & 255u) == 0u) { if (xb_ld(&(bar)[XB_TMO])) break; if (_sp > XB_SPIN_CAP) { atomicAdd(&(bar)[XB_TMO], 1u); break; } } } } while (0)
; __device__ __forceinline__ void xcd_barrier(const XcdBarrier& b) {
;     ...
;         const unsigned old = xb_add(&bar[XB_XSUB(b.x)], 1u);
;         const unsigned gen = old / nloc;
;         if (old + 1u == (gen + 1u) * nloc) {
;             __builtin_amdgcn_fence(__ATOMIC_RELEASE, "agent");
;             asm volatile("s_waitcnt vmcnt(0)" ::: "memory");
;             const unsigned og = xb_add(&bar[XB_TOP], 1u);
;             const unsigned tg = og / nx;
;             if (og + 1u == (tg + 1u) * nx) xb_add(&bar[XB_TOPGEN], 1u);
;             else XB_SPIN(xb_ld(&bar[XB_TOPGEN]) == tg, bar);
;             __builtin_amdgcn_fence(__ATOMIC_ACQUIRE, "agent");
;             xb_add(&bar[XB_XGEN(b.x)], 1u);
;             asm volatile("s_waitcnt vmcnt(0)" ::: "memory");
;         } else {
;             XB_SPIN(xb_ld(&bar[XB_XGEN(b.x)]) == gen, bar);
.LBB0_1778:
	s_or_b64 exec, exec, s[12:13]
	v_cvt_f32_u32_e32 v4, v2
	s_waitcnt vmcnt(0)
	v_readfirstlane_b32 s6, v3
	v_sub_u32_e32 v3, 0, v2
	v_rcp_iflag_f32_e32 v4, v4
	v_add_u32_e32 v5, s6, v1
	v_mul_f32_e32 v4, 0x4f7ffffe, v4
	v_cvt_u32_f32_e32 v4, v4
	v_mul_lo_u32 v1, v3, v4
	v_mul_hi_u32 v1, v4, v1
	v_add_u32_e32 v1, v4, v1
	v_mul_hi_u32 v1, v5, v1
	v_mul_lo_u32 v3, v1, v2
	v_sub_u32_e32 v3, v5, v3
	v_add_u32_e32 v4, 1, v1
	v_cmp_ge_u32_e32 vcc, v3, v2
	s_nop 1
	v_cndmask_b32_e32 v1, v1, v4, vcc
	v_sub_u32_e32 v4, v3, v2
	v_cndmask_b32_e32 v3, v3, v4, vcc
	v_add_u32_e32 v4, 1, v1
	v_cmp_ge_u32_e32 vcc, v3, v2
	v_add_u32_e32 v3, 1, v5
	s_nop 0
	v_cndmask_b32_e32 v1, v1, v4, vcc
	v_mul_lo_u32 v4, v2, v1
	v_add_u32_e32 v2, v4, v2
	v_cmp_ne_u32_e32 vcc, v3, v2
	s_and_saveexec_b64 s[6:7], vcc
	s_xor_b64 s[6:7], exec, s[6:7]
	s_cbranch_execz .LBB0_1792
	s_waitcnt lgkmcnt(0)
	v_mov_b32_e32 v0, 0x3000
	global_load_dword v0, v0, s[28:29] offset:1280 sc1
	s_add_u32 s14, s28, 0x3500
	s_addc_u32 s15, s29, 0
	s_waitcnt vmcnt(0)
	v_cmp_eq_u32_e32 vcc, v0, v1
	s_and_saveexec_b64 s[12:13], vcc
	s_cbranch_execz .LBB0_1791
	s_mov_b32 s21, 1
	s_mov_b64 s[16:17], 0
	v_mov_b32_e32 v0, 0
	s_branch .LBB0_1782
